# v24 + prompt-MLA loop: removed the early vmcnt(2/1/0) waits before the prefetch address computation at the top of each iteration (the in-flight loads target other registers and are waited at their LDS
# speedup vs baseline: 1.0008x; 1.0008x over previous
; #define GAS __attribute__((address_space(1)))
; #define LAS __attribute__((address_space(3)))
; template <int MODE> __device__ __forceinline__ void tile_loads(const AU& U, const TL& C, int T, v4u (&pre)[3]) {
;     ...
;         for (int i = 0; i < NLD; ++i) { const unsigned long long src = useA ? C.a[i] + (unsigned long long)tt * (unsigned long long)C.sa[i] : C.b[i] + (unsigned long long)tt * (unsigned long long)C.sb[i]; pre[i] = *(const GAS v4u*)src; }
;     }
; }
; template <int MODE> __device__ __forceinline__ void tile_stores(LAS unsigned char* buf, const TL& C, const v4u (&pre)[3]) {
;     constexpr int NLD = ((MODE == 0 ? 20 : 16) * 64 + 511) / 512;
; #pragma unroll
;     for (int i = 0; i < NLD; ++i) *(LAS v4u*)(buf + C.ld[i]) = pre[i];
; }
;     constexpr int NS = MODE == 0 ? 6 : 4, KSTR = MODE == 0 ? 208 : 144;
;     const LAS unsigned char* kb = buf + r * KSTR + hi * 16;
; #pragma unroll
;     for (int s = 0; s < NS; ++s) { const bf16x8 a0 = *(const LAS bf16x8*)(kb + 32 * s), a1 = *(const LAS bf16x8*)(kb + 32 * KSTR + 32 * s);
;         if (s == 0) { s0 = MFMA32(a0, qf[0], negm); s1 = MFMA32(a1, qf[0], negm); }
;         else { s0 = MFMA32(a0, qf[s], s0); s1 = MFMA32(a1, qf[s], s1); } }
; }
; template <int MODE> __device__ __forceinline__ void st_sm(int T, int tq, int qpos, int hi, const LAS float* biasl, f32x16& s0, f32x16& s1, f32x16& o0, f32x16& o1, f32x16& negm, float& lrun, bool& fresh) {
;     const float c2 = 0.125f * LOG2E;
;     if (MODE == 1) {
;         if (T + 5 <= tq) { const float cb = biasl[0];
; #pragma unroll
;             for (int i = 0; i < 16; ++i) { s0[i] = s0[i] * c2 + cb; s1[i] = s1[i] * c2 + cb; } }
;         else if (T + 3 >= tq) { const volatile LAS float* bp = biasl + (256 - qpos + T * 64 + 4 * hi);
; #pragma unroll
;             for (int i = 0; i < 16; ++i) { s0[i] = s0[i] * c2 + bp[(i & 3) + 8 * (i >> 2)]; s1[i] = s1[i] * c2 + bp[(i & 3) + 8 * (i >> 2) + 32]; } }
;         else {
; #pragma unroll
;             for (int i = 0; i < 16; ++i) { const int d0 = qpos - (T * 64 + crow(i, hi)); const int i0 = 256 - min(max(d0, -63), 256), i1 = 256 - min(max(d0 - 32, -63), 256);
;                 s0[i] = s0[i] * c2 + biasl[i0]; s1[i] = s1[i] * c2 + biasl[i1]; } }
;     }
;     ...
;     float ma = MX3_(s0[0], s0[1], s1[0]), mb = MX3_(s0[2], s0[3], s1[1]); ma = MX3_(ma, s1[2], s1[3]);
; #pragma unroll
.LBB0_666:
	s_add_i32 s0, s11, 1
	s_min_i32 s6, s0, s3
	v_mad_i64_i32 v[4:5], s[0:1], v170, s6, v[180:181]
	v_mad_i64_i32 v[8:9], s[0:1], v172, s6, v[178:179]
	v_mad_i64_i32 v[12:13], s[0:1], v174, s6, v[176:177]
	global_load_dwordx4 v[4:7], v[4:5], off
	s_add_i32 s13, s11, -1
	global_load_dwordx4 v[8:11], v[8:9], off
	s_cmp_le_i32 s13, s10
	global_load_dwordx4 v[12:15], v[12:13], off
	s_cselect_b64 s[0:1], -1, 0
	s_and_b64 s[0:1], s[8:9], s[0:1]
	s_andn2_b64 vcc, exec, s[0:1]
	s_cbranch_vccnz .LBB0_674
	v_add_u32_e32 v2, v171, v168
	s_xor_b64 s[0:1], s[4:5], -1
	s_and_b64 vcc, exec, s[0:1]
	ds_read_b128 v[66:69], v2
	ds_read_b128 v[134:137], v2 offset:6656
	ds_read_b128 v[138:141], v2 offset:32
	ds_read_b128 v[142:145], v2 offset:6688
	ds_read_b128 v[146:149], v2 offset:64
	ds_read_b128 v[150:153], v2 offset:6720
	ds_read_b128 v[154:157], v2 offset:96
	ds_read_b128 v[158:161], v2 offset:6752
	ds_read_b128 v[162:165], v2 offset:128
	s_waitcnt lgkmcnt(8)
	v_mfma_f32_32x32x16_bf16 v[82:97], v[66:69], v[110:113], v[50:65]
	s_waitcnt lgkmcnt(7)
	v_mfma_f32_32x32x16_bf16 v[66:81], v[134:137], v[110:113], v[50:65]
	ds_read_b128 v[134:137], v2 offset:6784
	s_waitcnt lgkmcnt(7)
	v_mfma_f32_32x32x16_bf16 v[82:97], v[138:141], v[106:109], v[82:97]
	ds_read_b128 v[138:141], v2 offset:160
	s_waitcnt lgkmcnt(7)
	v_mfma_f32_32x32x16_bf16 v[66:81], v[142:145], v[106:109], v[66:81]
	ds_read_b128 v[142:145], v2 offset:6816
	v_add_u32_e32 v2, 0x100, v183
	s_waitcnt lgkmcnt(7)
	v_mfma_f32_32x32x16_bf16 v[82:97], v[146:149], v[102:105], v[82:97]
	s_waitcnt lgkmcnt(6)
	v_mfma_f32_32x32x16_bf16 v[66:81], v[150:153], v[102:105], v[66:81]
	s_waitcnt lgkmcnt(5)
	v_mfma_f32_32x32x16_bf16 v[82:97], v[154:157], v[98:101], v[82:97]
	s_waitcnt lgkmcnt(4)
	v_mfma_f32_32x32x16_bf16 v[66:81], v[158:161], v[98:101], v[66:81]
	s_waitcnt lgkmcnt(3)
	v_mfma_f32_32x32x16_bf16 v[82:97], v[162:165], v[118:121], v[82:97]
	s_waitcnt lgkmcnt(2)
	v_mfma_f32_32x32x16_bf16 v[66:81], v[134:137], v[118:121], v[66:81]
	s_waitcnt lgkmcnt(1)
	v_mfma_f32_32x32x16_bf16 v[82:97], v[138:141], v[114:117], v[82:97]
	s_waitcnt lgkmcnt(0)
	v_mfma_f32_32x32x16_bf16 v[66:81], v[142:145], v[114:117], v[66:81]
	ds_read_b64_tr_b16 v[162:163], v2 offset:13312
	ds_read_b64_tr_b16 v[164:165], v2 offset:14848
	ds_read_b64_tr_b16 v[158:159], v2 offset:13376
	ds_read_b64_tr_b16 v[160:161], v2 offset:14912
	ds_read_b64_tr_b16 v[150:151], v2 offset:16384
	ds_read_b64_tr_b16 v[152:153], v2 offset:17920
	ds_read_b64_tr_b16 v[154:155], v2 offset:16448
	ds_read_b64_tr_b16 v[156:157], v2 offset:17984
	ds_read_b64_tr_b16 v[146:147], v2 offset:19456
	ds_read_b64_tr_b16 v[148:149], v2 offset:20992
	ds_read_b64_tr_b16 v[142:143], v2 offset:19520
	ds_read_b64_tr_b16 v[144:145], v2 offset:21056
	ds_read_b64_tr_b16 v[138:139], v2 offset:22528
	ds_read_b64_tr_b16 v[140:141], v2 offset:24064
	ds_read_b64_tr_b16 v[134:135], v2 offset:22592
	ds_read_b64_tr_b16 v[136:137], v2 offset:24128
	v_max_f32_e32 v2, v83, v83
	v_max_f32_e32 v16, v82, v82
	v_max_f32_e32 v2, v16, v2
	v_max3_f32 v16, v84, v85, v67
	v_max3_f32 v2, v2, v66, v68
	v_max3_f32 v2, v2, v69, v86
	v_max3_f32 v16, v16, v88, v89
	v_max3_f32 v2, v2, v87, v70
	v_max3_f32 v16, v16, v72, v73
	v_max3_f32 v2, v2, v71, v90
	v_max3_f32 v16, v16, v92, v93
	v_max3_f32 v2, v2, v91, v74
	v_max3_f32 v16, v16, v76, v77
	v_max3_f32 v2, v2, v75, v94
	v_max3_f32 v16, v16, v96, v97
	v_max3_f32 v2, v2, v95, v78
	v_max3_f32 v16, v16, v80, v81
	v_max3_f32 v2, v2, v79, v16
	v_mov_b32_e32 v16, v2
	s_nop 1
	v_permlane32_swap_b32_e32 v2, v16
	v_max_f32_e32 v2, v2, v16
	s_cbranch_vccz .Lrs0
	v_cmp_lt_f32_e32 vcc, s58, v2
	s_cmp_lg_u64 vcc, 0
	s_cbranch_scc0 .LBB0_673
